# l0_prep statistics loop: next token's five loads issued at the top of the current iteration (double buffer through copies)
# baseline (speedup 1.0000x reference)
; DI int ltid(int wv) { asm volatile("" : "+s"(wv)); int l = __builtin_amdgcn_mbcnt_hi(~0u, __builtin_amdgcn_mbcnt_lo(~0u, 0u)); asm volatile("" : "+v"(l)); return wv * 64 + l; }
; DI float bflo(unsigned u) { return __uint_as_float(u << 16); }
; DI float bfhi(unsigned u) { return __uint_as_float(u & 0xffff0000u); }
; DI void phase_l0_prep(int wv, const ArgP a) {
;     unsigned char* ws = a.ws();
;     const bf16_t* Z = (const bf16_t*)(ws + O_Z); bf16_t* XC = (bf16_t*)(ws + O_XC); bf16_t* KB = (bf16_t*)(ws + O_KB);
;     float* rsq = (float*)(ws + O_RSQ); float* rskv = (float*)(ws + O_RSKV); const float* cst = (const float*)(ws + O_CSTAB);
;     const float* cw = a.in(4); const float* cb = a.in(5);
;     const int tid = ltid(wv), wave = tid >> 6, lane = tid & 63;
;     ...
; #pragma unroll 4
;     for (int t = blockIdx.x * 8 + wave; t < S; t += gridDim.x * 8) {
;         const bf16_t* zr = Z + (size_t)t * 1536;
;         float sq = 0.f, skv = 0.f;
;         { const u32x2 v = *(const u32x2*)(zr + 1024 + lane * 4); const float p0 = bflo(v.x), p1 = bfhi(v.x), p2 = bflo(v.y), p3 = bfhi(v.y); sq = p0 * p0 + p1 * p1 + p2 * p2 + p3 * p3; }
.LBB0_462:
	s_or_b64 exec, exec, s[8:9]
	v_add_u32_e32 v0, 64, v196
	v_cmp_lt_i32_e32 vcc, v157, v0
	s_movk_i32 s4, 0x4000
	s_nop 0
	v_cndmask_b32_e32 v1, v192, v157, vcc
	v_cmp_lt_i32_e32 vcc, v156, v0
	v_lshlrev_b32_e32 v193, 2, v1
	s_nop 0
	v_cndmask_b32_e32 v1, v192, v156, vcc
	v_cmp_lt_i32_e32 vcc, v155, v0
	v_lshlrev_b32_e32 v194, 2, v1
	s_nop 0
	v_cndmask_b32_e32 v1, v192, v155, vcc
	v_cmp_lt_i32_e32 vcc, v154, v0
	v_lshlrev_b32_e32 v197, 2, v1
	s_nop 0
	v_cndmask_b32_e32 v1, v192, v154, vcc
	v_cmp_lt_i32_e32 vcc, v153, v0
	v_lshlrev_b32_e32 v198, 2, v1
	s_nop 0
	v_cndmask_b32_e32 v1, v192, v153, vcc
	v_cmp_lt_i32_e32 vcc, v152, v0
	v_lshlrev_b32_e32 v199, 2, v1
	s_nop 0
	v_cndmask_b32_e32 v0, v192, v152, vcc
	v_lshlrev_b32_e32 v195, 2, v0
	v_ashrrev_i32_e32 v0, 6, v19
	v_add_u32_e32 v0, s46, v0
	v_cmp_gt_i32_e32 vcc, s4, v0
	s_and_saveexec_b64 s[10:11], vcc
	s_cbranch_execz .LBB0_469
	s_load_dword s16, s[88:89], 0x0
	s_add_u32 s12, s0, 0x1920000
	v_and_b32_e32 v14, 63, v18
	s_addc_u32 s13, s1, 0
	v_mov_b32_e32 v3, 0
	v_lshlrev_b32_e32 v10, 1, v14
	v_lshlrev_b32_e32 v2, 3, v14
	s_add_u32 s14, s0, 0x1930000
	v_lshlrev_b32_e32 v8, 2, v14
	v_lshl_add_u64 v[4:5], s[0:1], 0, v[2:3]
	s_mov_b64 s[8:9], 0x1940000
	v_mov_b64_e32 v[6:7], s[2:3]
	v_lshlrev_b32_e32 v10, 1, v10
	s_brev_b32 s2, 60
	s_addc_u32 s15, s1, 0
	v_cmp_eq_u32_e64 s[4:5], 0, v14
	v_cmp_gt_u32_e64 s[6:7], 16, v14
	v_lshl_add_u64 v[4:5], v[4:5], 0, s[8:9]
	s_waitcnt lgkmcnt(0)
	s_lshl_b32 s20, s16, 3
	s_mov_b64 s[16:17], 0
	s_movk_i32 s21, 0xc00
	v_lshlrev_b32_e32 v8, 1, v8
	v_mov_b32_e32 v9, v3
	v_mov_b32_e32 v12, v10
	v_mov_b32_e32 v13, v3
	s_mov_b32 s3, 0x3b800000
	s_mov_b32 s22, 0x800000
	v_lshlrev_b32_e32 v2, 1, v14
	s_movk_i32 s23, 0xc0
	s_mov_b32 s24, 0xad6b000
	s_mov_b32 s25, 0xb06b000
	s_mov_b32 s26, 0xb36b000
	s_mov_b32 s27, 0xb66b000
	s_movk_i32 s28, 0x3fff
	v_mov_b32_e32 v14, 0x358637bd
	v_mad_i64_i32 v[58:59], s[8:9], v0, s21, v[6:7]
	v_lshl_add_u64 v[60:61], v[58:59], 0, v[8:9]
	global_load_dwordx2 v[48:49], v[60:61], off offset:2048
	v_lshl_add_u64 v[60:61], v[58:59], 0, v[12:13]
	global_load_dword v50, v[60:61], off offset:2560
	v_mov_b32_e32 v44, v0
	v_ashrrev_i32_e32 v45, 31, v0
	v_lshl_add_u64 v[46:47], v[58:59], 0, v[2:3]
	v_lshlrev_b64 v[44:45], 7, v[44:45]
	v_lshl_add_u64 v[44:45], v[4:5], 0, v[44:45]
	s_and_saveexec_b64 s[18:19], s[6:7]
	global_load_ushort v51, v[46:47], off offset:2816
	global_load_ushort v52, v[46:47], off offset:2848
	global_load_dwordx2 v[54:55], v[44:45], off
	s_or_b64 exec, exec, s[18:19]
	s_waitcnt vmcnt(0)
	s_branch .LBB0_465
.LBB0_464:
	s_or_b64 exec, exec, s[8:9]
	s_waitcnt vmcnt(10)
	v_add_u32_e32 v0, s20, v0
	v_cmp_lt_i32_e32 vcc, s28, v0
	s_or_b64 s[16:17], vcc, s[16:17]
	s_andn2_b64 exec, exec, s[16:17]
	s_cbranch_execz .LBB0_469
; DI unsigned pk2(float lo, float hi) { f32x2 v = {lo, hi}; bf16x2_t b = __builtin_convertvector(v, bf16x2_t); return __builtin_bit_cast(unsigned, b); }
; DI float bf2f(bf16_t b) { return __uint_as_float(((unsigned)b) << 16); }
; DI float bflo(unsigned u) { return __uint_as_float(u << 16); }
; DI float bfhi(unsigned u) { return __uint_as_float(u & 0xffff0000u); }
; DI void phase_l0_prep(int wv, const ArgP a) {
;     ...
;     for (int t = blockIdx.x * 8 + wave; t < S; t += gridDim.x * 8) {
;         const bf16_t* zr = Z + (size_t)t * 1536;
;         float sq = 0.f, skv = 0.f;
;         { const u32x2 v = *(const u32x2*)(zr + 1024 + lane * 4); const float p0 = bflo(v.x), p1 = bfhi(v.x), p2 = bflo(v.y), p3 = bfhi(v.y); sq = p0 * p0 + p1 * p1 + p2 * p2 + p3 * p3; }
;         { const unsigned v = *(const unsigned*)(zr + 1280 + lane * 2); const float p0 = bflo(v), p1 = bfhi(v); skv = p0 * p0 + p1 * p1; }
;         sq = wave_sum(sq); skv = wave_sum(skv);
;         if (lane == 0) { rsq[t] = rsqrtf(sq * (1.f / 256.f) + EPS); rskv[t] = rsqrtf(skv * (1.f / 128.f) + EPS); }
;         if (lane < 16) { const float x1 = bf2f(zr[1408 + lane]), x2 = bf2f(zr[1424 + lane]); const float c = cst[(size_t)t * 32 + 2 * lane], s = cst[(size_t)t * 32 + 2 * lane + 1];
;             const unsigned w = pk2(x1 * c - x2 * s, x2 * c + x1 * s);
; #pragma unroll
;             for (int h = 0; h < 8; ++h) *(unsigned*)(KB + ((size_t)h * S + t) * 96 + 64 + 2 * lane) = w; }
;     }
.LBB0_465:
	v_mov_b64_e32 v[18:19], v[48:49]
	v_mov_b32_e32 v1, v50
	v_mov_b32_e32 v40, v51
	v_mov_b32_e32 v41, v52
	v_mov_b64_e32 v[42:43], v[54:55]
	v_add_u32_e32 v56, s20, v0
	v_cmp_lt_i32_e32 vcc, s28, v56
	s_nop 1
	v_cndmask_b32_e32 v56, v56, v0, vcc
	v_mad_i64_i32 v[58:59], s[8:9], v56, s21, v[6:7]
	v_lshl_add_u64 v[60:61], v[58:59], 0, v[8:9]
	global_load_dwordx2 v[48:49], v[60:61], off offset:2048
	v_lshl_add_u64 v[60:61], v[58:59], 0, v[12:13]
	global_load_dword v50, v[60:61], off offset:2560
	v_mov_b32_e32 v44, v56
	v_ashrrev_i32_e32 v45, 31, v56
	v_lshl_add_u64 v[46:47], v[58:59], 0, v[2:3]
	v_lshlrev_b64 v[44:45], 7, v[44:45]
	v_lshl_add_u64 v[44:45], v[4:5], 0, v[44:45]
	s_and_saveexec_b64 s[18:19], s[6:7]
	global_load_ushort v51, v[46:47], off offset:2816
	global_load_ushort v52, v[46:47], off offset:2848
	global_load_dwordx2 v[54:55], v[44:45], off
	s_or_b64 exec, exec, s[18:19]
	v_and_b32_e32 v11, 0xffff0000, v18
	v_and_b32_e32 v21, 0xffff0000, v19
	v_lshlrev_b32_e32 v19, 16, v19
	v_lshlrev_b32_e32 v18, 16, v18
	v_lshlrev_b32_e32 v20, 16, v1
	v_and_b32_e32 v1, 0xffff0000, v1
	v_pk_mul_f32 v[18:19], v[18:19], v[18:19]
	v_mul_f32_e32 v22, v1, v1
	v_fma_f32 v1, v11, v11, v18
	v_add_f32_e32 v23, v19, v1
	v_pk_fma_f32 v[18:19], v[20:21], v[20:21], v[22:23]
	v_ashrrev_i32_e32 v1, 31, v0
	s_nop 1
	v_add_f32_dpp v18, v18, v18 quad_perm:[1,0,3,2] row_mask:0xf bank_mask:0xf
	v_add_f32_dpp v19, v19, v19 quad_perm:[1,0,3,2] row_mask:0xf bank_mask:0xf
	s_nop 1
	v_add_f32_dpp v18, v18, v18 quad_perm:[2,3,0,1] row_mask:0xf bank_mask:0xf
	v_add_f32_dpp v19, v19, v19 quad_perm:[2,3,0,1] row_mask:0xf bank_mask:0xf
	s_nop 1
	v_add_f32_dpp v18, v18, v18 row_half_mirror row_mask:0xf bank_mask:0xf
	v_add_f32_dpp v19, v19, v19 row_half_mirror row_mask:0xf bank_mask:0xf
	s_nop 1
	v_add_f32_dpp v18, v18, v18 row_mirror row_mask:0xf bank_mask:0xf
	v_add_f32_dpp v19, v19, v19 row_mirror row_mask:0xf bank_mask:0xf
	s_nop 1
	v_readlane_b32 s29, v18, 16
	v_readlane_b32 s30, v19, 16
	v_readlane_b32 s31, v18, 32
	v_readlane_b32 s32, v19, 32
	v_readlane_b32 s33, v18, 48
	v_readlane_b32 s34, v19, 48
	s_nop 1
	v_add_f32_e32 v18, s29, v18
	v_add_f32_e32 v19, s30, v19
	v_add_f32_e32 v18, s31, v18
	v_add_f32_e32 v19, s32, v19
	v_add_f32_e32 v18, s33, v18
	v_add_f32_e32 v19, s34, v19
	s_and_saveexec_b64 s[18:19], s[4:5]
	s_cbranch_execz .LBB0_467
	v_lshlrev_b64 v[22:23], 2, v[0:1]
	v_pk_fma_f32 v[18:19], v[18:19], s[2:3], v[14:15] op_sel_hi:[1,1,0]
	v_lshl_add_u64 v[24:25], s[12:13], 0, v[22:23]
	v_mul_f32_e32 v11, 0x4b800000, v19
	v_cmp_gt_f32_e32 vcc, s22, v19
	v_mul_f32_e32 v15, 0x4b800000, v18
	v_cmp_gt_f32_e64 s[8:9], s22, v18
	v_cndmask_b32_e32 v11, v19, v11, vcc
	v_rsq_f32_e32 v11, v11
	v_cndmask_b32_e64 v15, v18, v15, s[8:9]
	v_rsq_f32_e32 v15, v15
	v_mul_f32_e32 v18, 0x45800000, v11
	v_cndmask_b32_e32 v11, v11, v18, vcc
	global_store_dword v[24:25], v11, off
	v_mul_f32_e32 v11, 0x45800000, v15
	v_cndmask_b32_e64 v11, v15, v11, s[8:9]
	v_lshl_add_u64 v[18:19], s[14:15], 0, v[22:23]
	global_store_dword v[18:19], v11, off
.LBB0_467:
	s_or_b64 exec, exec, s[18:19]
	s_and_saveexec_b64 s[8:9], s[6:7]
	s_cbranch_execz .LBB0_464
	s_waitcnt lgkmcnt(0)
	v_mov_b64_e32 v[16:17], s[0:1]
	v_mov_b32_e32 v11, v3
	v_mad_i64_i32 v[16:17], s[18:19], v0, s23, v[16:17]
	v_lshl_add_u64 v[16:17], v[16:17], 0, v[10:11]
	v_add_co_u32_e32 v18, vcc, s24, v16
	v_lshlrev_b32_e32 v34, 16, v40
	v_addc_co_u32_e32 v19, vcc, 0, v17, vcc
	v_add_co_u32_e32 v22, vcc, s25, v16
	v_lshlrev_b32_e32 v36, 16, v41
	v_addc_co_u32_e32 v23, vcc, 0, v17, vcc
	v_add_co_u32_e32 v24, vcc, s26, v16
	v_pk_mul_f32 v[36:37], v[42:43], v[36:37] op_sel:[1,0] op_sel_hi:[0,0]
	v_addc_co_u32_e32 v25, vcc, 0, v17, vcc
	v_add_co_u32_e32 v26, vcc, s27, v16
	v_pk_fma_f32 v[38:39], v[42:43], v[34:35], v[36:37] neg_lo:[0,0,1] neg_hi:[0,0,1]
	s_nop 0
	v_addc_co_u32_e32 v27, vcc, 0, v17, vcc
	v_add_co_u32_e32 v28, vcc, 0xb96b000, v16
	v_pk_fma_f32 v[20:21], v[42:43], v[34:35], v[36:37] op_sel_hi:[1,0,1]
	s_nop 0
	v_addc_co_u32_e32 v29, vcc, 0, v17, vcc
	v_add_co_u32_e32 v30, vcc, 0xbc6b000, v16
	v_cvt_pk_bf16_f32 v1, v38, v21
	s_nop 0
	v_addc_co_u32_e32 v31, vcc, 0, v17, vcc
	v_add_co_u32_e32 v32, vcc, 0xbf6b000, v16
	s_nop 1
	v_addc_co_u32_e32 v33, vcc, 0, v17, vcc
	v_add_co_u32_e32 v16, vcc, 0xc26b000, v16
	s_nop 1
	v_addc_co_u32_e32 v17, vcc, 0, v17, vcc
	global_store_dword v[18:19], v1, off offset:128
	global_store_dword v[22:23], v1, off offset:128
	global_store_dword v[24:25], v1, off offset:128
	global_store_dword v[26:27], v1, off offset:128
	global_store_dword v[28:29], v1, off offset:128
	global_store_dword v[30:31], v1, off offset:128
	global_store_dword v[32:33], v1, off offset:128
	global_store_dword v[16:17], v1, off offset:128
	s_branch .LBB0_464
